# v47 + P3 steady steps: the eight per-MFMA LDS waits of the P.V section folded into one lgkmcnt(0) at its head
# speedup vs baseline: 1.0200x; 1.0001x over previous
.LBB0_1606:
	s_waitcnt lgkmcnt(0)
	v_mfma_f32_32x32x16_bf16 v[32:47], v[140:143], v[6:9], v[32:47]
	v_exp_f32_e32 v96, v96
	v_exp_f32_e32 v97, v97
	v_exp_f32_e32 v98, v98
	v_exp_f32_e32 v99, v99
	v_mfma_f32_32x32x16_bf16 v[16:31], v[140:143], v[2:5], v[16:31]
	v_exp_f32_e32 v100, v100
	v_exp_f32_e32 v101, v101
	v_exp_f32_e32 v102, v102
	v_exp_f32_e32 v103, v103
	v_add_u32_e32 v0, s34, v199
	ds_read_b128 v[6:9], v0
	ds_read_b128 v[172:175], v0 offset:512
	v_mfma_f32_32x32x16_bf16 v[32:47], v[132:135], v[10:13], v[32:47]
	v_exp_f32_e32 v104, v104
	v_exp_f32_e32 v105, v105
	v_exp_f32_e32 v106, v106
	v_exp_f32_e32 v107, v107
	ds_read_b128 v[168:171], v0 offset:2048
	ds_read_b128 v[164:167], v0 offset:2560
	v_mfma_f32_32x32x16_bf16 v[16:31], v[132:135], v[64:67], v[16:31]
	v_exp_f32_e32 v108, v108
	v_exp_f32_e32 v109, v109
	v_exp_f32_e32 v110, v110
	v_exp_f32_e32 v111, v111
	ds_read_b128 v[160:163], v0 offset:4096
	ds_read_b128 v[156:159], v0 offset:4608
	v_mfma_f32_32x32x16_bf16 v[32:47], v[124:127], v[68:71], v[32:47]
	v_exp_f32_e32 v80, v80
	v_exp_f32_e32 v81, v81
	v_exp_f32_e32 v82, v82
	v_exp_f32_e32 v83, v83
	ds_read_b128 v[152:155], v0 offset:6144
	ds_read_b128 v[144:147], v0 offset:6656
	s_and_b32 s18, s30, 0x3fffffe0
	v_lshl_add_u32 v0, s18, 2, v194
	ds_read_b32 v48, v0 offset:49408
	v_mfma_f32_32x32x16_bf16 v[16:31], v[124:127], v[72:75], v[16:31]
	v_exp_f32_e32 v84, v84
	v_exp_f32_e32 v85, v85
	v_exp_f32_e32 v86, v86
	v_exp_f32_e32 v87, v87
	v_mfma_f32_32x32x16_bf16 v[32:47], v[120:123], v[76:79], v[32:47]
	v_exp_f32_e32 v88, v88
	v_exp_f32_e32 v89, v89
	v_exp_f32_e32 v90, v90
	v_exp_f32_e32 v91, v91
	v_mfma_f32_32x32x16_bf16 v[16:31], v[120:123], v[148:151], v[16:31]
	v_exp_f32_e32 v92, v92
	v_exp_f32_e32 v93, v93
	v_exp_f32_e32 v94, v94
	v_exp_f32_e32 v95, v95
	s_waitcnt vmcnt(2) lgkmcnt(0)
	s_barrier
	s_andn2_b64 vcc, exec, s[16:17]
	v_add_u32_e32 v0, s40, v201
	s_cbranch_vccnz .LBB0_1608
	s_waitcnt lgkmcnt(0)
	ds_read_b128 v[2:5], v0 offset:49248
	ds_read_b128 v[10:13], v0 offset:49216
	ds_read_b128 v[48:51], v0 offset:49184
	ds_read_b128 v[52:55], v0 offset:49152
	s_waitcnt lgkmcnt(3)
	v_pk_mul_f32 v[44:45], v[44:45], v[2:3]
	s_waitcnt lgkmcnt(2)
	v_pk_mul_f32 v[40:41], v[40:41], v[10:11]
	s_waitcnt lgkmcnt(1)
	v_pk_mul_f32 v[36:37], v[36:37], v[48:49]
	v_pk_mul_f32 v[46:47], v[46:47], v[4:5]
	v_pk_mul_f32 v[42:43], v[42:43], v[12:13]
	v_pk_mul_f32 v[38:39], v[38:39], v[50:51]
	s_waitcnt lgkmcnt(0)
	v_pk_mul_f32 v[34:35], v[34:35], v[54:55]
	v_pk_mul_f32 v[32:33], v[32:33], v[52:53]
	v_pk_mul_f32 v[28:29], v[28:29], v[2:3]
	v_pk_mul_f32 v[24:25], v[24:25], v[10:11]
	v_pk_mul_f32 v[20:21], v[20:21], v[48:49]
	v_pk_mul_f32 v[30:31], v[30:31], v[4:5]
	v_pk_mul_f32 v[26:27], v[26:27], v[12:13]
	v_pk_mul_f32 v[22:23], v[22:23], v[50:51]
	v_pk_mul_f32 v[18:19], v[18:19], v[54:55]
	v_pk_mul_f32 v[16:17], v[16:17], v[52:53]
	s_and_b32 s17, s30, 0x3fffffe0
	v_lshl_add_u32 v2, s17, 2, v194
	ds_read_b32 v48, v2 offset:49408
	s_waitcnt lgkmcnt(0)

.LBB0_1609:
	s_waitcnt lgkmcnt(0)
	v_mfma_f32_32x32x16_bf16 v[32:47], v[140:143], v[2:5], v[32:47]
	v_exp_f32_e32 v64, v64
	v_exp_f32_e32 v65, v65
	v_exp_f32_e32 v66, v66
	v_exp_f32_e32 v67, v67
	v_mfma_f32_32x32x16_bf16 v[16:31], v[140:143], v[6:9], v[16:31]
	v_exp_f32_e32 v68, v68
	v_exp_f32_e32 v69, v69
	v_exp_f32_e32 v70, v70
	v_exp_f32_e32 v71, v71
	v_add_u32_e32 v2, s29, v199
	ds_read_b128 v[172:175], v2
	ds_read_b128 v[168:171], v2 offset:512
	v_mfma_f32_32x32x16_bf16 v[32:47], v[132:135], v[10:13], v[32:47]
	v_exp_f32_e32 v72, v72
	v_exp_f32_e32 v73, v73
	v_exp_f32_e32 v74, v74
	v_exp_f32_e32 v75, v75
	ds_read_b128 v[164:167], v2 offset:2048
	ds_read_b128 v[160:163], v2 offset:2560
	v_mfma_f32_32x32x16_bf16 v[16:31], v[132:135], v[96:99], v[16:31]
	v_exp_f32_e32 v76, v76
	v_exp_f32_e32 v77, v77
	v_exp_f32_e32 v78, v78
	v_exp_f32_e32 v79, v79
	ds_read_b128 v[156:159], v2 offset:4096
	ds_read_b128 v[152:155], v2 offset:4608
	v_mfma_f32_32x32x16_bf16 v[32:47], v[124:127], v[100:103], v[32:47]
	v_exp_f32_e32 v48, v48
	v_exp_f32_e32 v49, v49
	v_exp_f32_e32 v50, v50
	v_exp_f32_e32 v51, v51
	ds_read_b128 v[148:151], v2 offset:6144
	ds_read_b128 v[144:147], v2 offset:6656
	s_add_i32 s18, s30, 1
	s_and_b32 s18, s18, 0x3fffffe0
	v_lshl_add_u32 v2, s18, 2, v194
	ds_read_b32 v80, v2 offset:49408
	v_mfma_f32_32x32x16_bf16 v[16:31], v[124:127], v[104:107], v[16:31]
	v_exp_f32_e32 v52, v52
	v_exp_f32_e32 v53, v53
	v_exp_f32_e32 v54, v54
	v_exp_f32_e32 v55, v55
	v_mfma_f32_32x32x16_bf16 v[32:47], v[120:123], v[108:111], v[32:47]
	v_exp_f32_e32 v56, v56
	v_exp_f32_e32 v57, v57
	v_exp_f32_e32 v58, v58
	v_exp_f32_e32 v59, v59
	v_mfma_f32_32x32x16_bf16 v[16:31], v[120:123], v[176:179], v[16:31]
	v_exp_f32_e32 v60, v60
	v_exp_f32_e32 v61, v61
	v_exp_f32_e32 v62, v62
	v_exp_f32_e32 v63, v63
	s_waitcnt vmcnt(2) lgkmcnt(0)
	s_barrier
	s_andn2_b64 vcc, exec, s[16:17]
	s_cbranch_vccnz .LBB0_1611
	s_waitcnt lgkmcnt(0)
	ds_read_b128 v[2:5], v0 offset:49248
	ds_read_b128 v[6:9], v0 offset:49216
	ds_read_b128 v[10:13], v0 offset:49184
	ds_read_b128 v[80:83], v0 offset:49152
	s_waitcnt lgkmcnt(3)
	v_pk_mul_f32 v[44:45], v[44:45], v[2:3]
	s_waitcnt lgkmcnt(2)
	v_pk_mul_f32 v[40:41], v[40:41], v[6:7]
	s_waitcnt lgkmcnt(1)
	v_pk_mul_f32 v[36:37], v[36:37], v[10:11]
	v_pk_mul_f32 v[46:47], v[46:47], v[4:5]
	v_pk_mul_f32 v[42:43], v[42:43], v[8:9]
	v_pk_mul_f32 v[38:39], v[38:39], v[12:13]
	s_waitcnt lgkmcnt(0)
	v_pk_mul_f32 v[34:35], v[34:35], v[82:83]
	v_pk_mul_f32 v[32:33], v[32:33], v[80:81]
	v_pk_mul_f32 v[28:29], v[28:29], v[2:3]
	v_pk_mul_f32 v[24:25], v[24:25], v[6:7]
	v_pk_mul_f32 v[20:21], v[20:21], v[10:11]
	v_pk_mul_f32 v[30:31], v[30:31], v[4:5]
	v_pk_mul_f32 v[26:27], v[26:27], v[8:9]
	v_pk_mul_f32 v[22:23], v[22:23], v[12:13]
	v_pk_mul_f32 v[18:19], v[18:19], v[82:83]
	v_pk_mul_f32 v[16:17], v[16:17], v[80:81]
	s_add_i32 s17, s30, 1
	s_and_b32 s17, s17, 0x3fffffe0
	v_lshl_add_u32 v2, s17, 2, v194
	ds_read_b32 v80, v2 offset:49408
	s_waitcnt lgkmcnt(0)

.LBB0_1690:
	s_waitcnt lgkmcnt(0)
	v_mfma_f32_32x32x16_bf16 v[32:47], v[156:159], v[192:195], v[32:47]
	v_exp_f32_e32 v112, v112
	v_exp_f32_e32 v113, v113
	v_exp_f32_e32 v114, v114
	v_exp_f32_e32 v115, v115
	v_mfma_f32_32x32x16_bf16 v[16:31], v[156:159], v[80:83], v[16:31]
	v_exp_f32_e32 v116, v116
	v_exp_f32_e32 v117, v117
	v_exp_f32_e32 v118, v118
	v_exp_f32_e32 v119, v119
	v_add_u32_e32 v14, s18, v226
	ds_read_b128 v[76:79], v14
	ds_read_b128 v[184:187], v14 offset:512
	v_mfma_f32_32x32x16_bf16 v[32:47], v[152:155], v[2:5], v[32:47]
	v_exp_f32_e32 v120, v120
	v_exp_f32_e32 v121, v121
	v_exp_f32_e32 v122, v122
	v_exp_f32_e32 v123, v123
	ds_read_b128 v[188:191], v14 offset:2048
	ds_read_b128 v[180:183], v14 offset:2560
	v_mfma_f32_32x32x16_bf16 v[16:31], v[152:155], v[6:9], v[16:31]
	v_exp_f32_e32 v124, v124
	v_exp_f32_e32 v125, v125
	v_exp_f32_e32 v126, v126
	v_exp_f32_e32 v127, v127
	ds_read_b128 v[176:179], v14 offset:4096
	ds_read_b128 v[172:175], v14 offset:4608
	v_mfma_f32_32x32x16_bf16 v[32:47], v[148:151], v[10:13], v[32:47]
	v_exp_f32_e32 v96, v96
	v_exp_f32_e32 v97, v97
	v_exp_f32_e32 v98, v98
	v_exp_f32_e32 v99, v99
	ds_read_b128 v[168:171], v14 offset:6144
	ds_read_b128 v[164:167], v14 offset:6656
	v_mfma_f32_32x32x16_bf16 v[16:31], v[148:151], v[64:67], v[16:31]
	v_exp_f32_e32 v100, v100
	v_exp_f32_e32 v101, v101
	v_exp_f32_e32 v102, v102
	v_exp_f32_e32 v103, v103
	v_mfma_f32_32x32x16_bf16 v[32:47], v[144:147], v[68:71], v[32:47]
	v_exp_f32_e32 v104, v104
	v_exp_f32_e32 v105, v105
	v_exp_f32_e32 v106, v106
	v_exp_f32_e32 v107, v107
	v_mfma_f32_32x32x16_bf16 v[16:31], v[144:147], v[72:75], v[16:31]
	v_exp_f32_e32 v108, v108
	v_exp_f32_e32 v109, v109
	v_exp_f32_e32 v110, v110
	v_exp_f32_e32 v111, v111
	s_waitcnt vmcnt(2) lgkmcnt(0)
	s_barrier
	s_andn2_b64 vcc, exec, s[14:15]
	s_cbranch_vccnz .LBB0_1692
	s_waitcnt lgkmcnt(0)
	ds_read_b128 v[2:5], v198 offset:49248
	ds_read_b128 v[6:9], v198 offset:49216
	ds_read_b128 v[10:13], v198 offset:49184
	ds_read_b128 v[64:67], v198 offset:49152
	s_waitcnt lgkmcnt(3)
	v_pk_mul_f32 v[44:45], v[44:45], v[2:3]
	s_waitcnt lgkmcnt(2)
	v_pk_mul_f32 v[40:41], v[40:41], v[6:7]
	s_waitcnt lgkmcnt(1)
	v_pk_mul_f32 v[36:37], v[36:37], v[10:11]
	v_pk_mul_f32 v[46:47], v[46:47], v[4:5]
	v_pk_mul_f32 v[42:43], v[42:43], v[8:9]
	v_pk_mul_f32 v[38:39], v[38:39], v[12:13]
	s_waitcnt lgkmcnt(0)
	v_pk_mul_f32 v[34:35], v[34:35], v[66:67]
	v_pk_mul_f32 v[32:33], v[32:33], v[64:65]
	v_pk_mul_f32 v[28:29], v[28:29], v[2:3]
	v_pk_mul_f32 v[24:25], v[24:25], v[6:7]
	v_pk_mul_f32 v[20:21], v[20:21], v[10:11]
	v_pk_mul_f32 v[30:31], v[30:31], v[4:5]
	v_pk_mul_f32 v[26:27], v[26:27], v[8:9]
	v_pk_mul_f32 v[22:23], v[22:23], v[12:13]
	v_pk_mul_f32 v[18:19], v[18:19], v[66:67]
	v_pk_mul_f32 v[16:17], v[16:17], v[64:65]

.LBB0_1695:
	s_waitcnt lgkmcnt(0)
	v_mfma_f32_32x32x16_bf16 v[32:47], v[156:159], v[160:163], v[32:47]
	v_exp_f32_e32 v80, v80
	v_exp_f32_e32 v81, v81
	v_exp_f32_e32 v82, v82
	v_exp_f32_e32 v83, v83
	v_mfma_f32_32x32x16_bf16 v[16:31], v[156:159], v[112:115], v[16:31]
	v_exp_f32_e32 v84, v84
	v_exp_f32_e32 v85, v85
	v_exp_f32_e32 v86, v86
	v_exp_f32_e32 v87, v87
	v_add_u32_e32 v0, s26, v226
	ds_read_b128 v[188:191], v0
	ds_read_b128 v[184:187], v0 offset:512
	v_mfma_f32_32x32x16_bf16 v[32:47], v[152:155], v[2:5], v[32:47]
	v_exp_f32_e32 v88, v88
	v_exp_f32_e32 v89, v89
	v_exp_f32_e32 v90, v90
	v_exp_f32_e32 v91, v91
	ds_read_b128 v[180:183], v0 offset:2048
	ds_read_b128 v[176:179], v0 offset:2560
	v_mfma_f32_32x32x16_bf16 v[16:31], v[152:155], v[6:9], v[16:31]
	v_exp_f32_e32 v92, v92
	v_exp_f32_e32 v93, v93
	v_exp_f32_e32 v94, v94
	v_exp_f32_e32 v95, v95
	ds_read_b128 v[172:175], v0 offset:4096
	ds_read_b128 v[168:171], v0 offset:4608
	v_mfma_f32_32x32x16_bf16 v[32:47], v[148:151], v[10:13], v[32:47]
	v_exp_f32_e32 v64, v64
	v_exp_f32_e32 v65, v65
	v_exp_f32_e32 v66, v66
	v_exp_f32_e32 v67, v67
	ds_read_b128 v[164:167], v0 offset:6144
	ds_read_b128 v[160:163], v0 offset:6656
	v_mfma_f32_32x32x16_bf16 v[16:31], v[148:151], v[96:99], v[16:31]
	v_exp_f32_e32 v68, v68
	v_exp_f32_e32 v69, v69
	v_exp_f32_e32 v70, v70
	v_exp_f32_e32 v71, v71
	v_mfma_f32_32x32x16_bf16 v[32:47], v[144:147], v[100:103], v[32:47]
	v_exp_f32_e32 v72, v72
	v_exp_f32_e32 v73, v73
	v_exp_f32_e32 v74, v74
	v_exp_f32_e32 v75, v75
	v_mfma_f32_32x32x16_bf16 v[16:31], v[144:147], v[104:107], v[16:31]
	v_exp_f32_e32 v76, v76
	v_exp_f32_e32 v77, v77
	v_exp_f32_e32 v78, v78
	v_exp_f32_e32 v79, v79
	s_waitcnt vmcnt(2) lgkmcnt(0)
	s_barrier
	s_andn2_b64 vcc, exec, s[14:15]
	s_cbranch_vccnz .LBB0_1697
	s_waitcnt lgkmcnt(0)
	ds_read_b128 v[2:5], v198 offset:49248
	ds_read_b128 v[6:9], v198 offset:49216
	ds_read_b128 v[10:13], v198 offset:49184
	ds_read_b128 v[96:99], v198 offset:49152
	s_waitcnt lgkmcnt(3)
	v_pk_mul_f32 v[44:45], v[44:45], v[2:3]
	s_waitcnt lgkmcnt(2)
	v_pk_mul_f32 v[40:41], v[40:41], v[6:7]
	s_waitcnt lgkmcnt(1)
	v_pk_mul_f32 v[36:37], v[36:37], v[10:11]
	v_pk_mul_f32 v[46:47], v[46:47], v[4:5]
	v_pk_mul_f32 v[42:43], v[42:43], v[8:9]
	v_pk_mul_f32 v[38:39], v[38:39], v[12:13]
	s_waitcnt lgkmcnt(0)
	v_pk_mul_f32 v[34:35], v[34:35], v[98:99]
	v_pk_mul_f32 v[32:33], v[32:33], v[96:97]
	v_pk_mul_f32 v[28:29], v[28:29], v[2:3]
	v_pk_mul_f32 v[24:25], v[24:25], v[6:7]
	v_pk_mul_f32 v[20:21], v[20:21], v[10:11]
	v_pk_mul_f32 v[30:31], v[30:31], v[4:5]
	v_pk_mul_f32 v[26:27], v[26:27], v[8:9]
	v_pk_mul_f32 v[22:23], v[22:23], v[12:13]
	v_pk_mul_f32 v[18:19], v[18:19], v[98:99]
	v_pk_mul_f32 v[16:17], v[16:17], v[96:97]
